# merge phase: both wave halves aligned by a conditional barrier pair around each K-seam (gate ratio rescale) so the two seams run concurrently instead of one after the other
# speedup vs baseline: 1.0218x; 1.0113x over previous
; __device__ __forceinline__ f32x4 un_unorm8(unsigned w) { return (f32x4){fmaxf((float)(w & 255u), 0.5f), fmaxf((float)((w >> 8) & 255u), 0.5f), fmaxf((float)((w >> 16) & 255u), 0.5f), fmaxf((float)(w >> 24), 0.5f)}; }
; #define EPI_OPAQUE asm volatile("" : "+v"(fr), "+v"(fq));
;     __device__ __forceinline__ void seam(f32x4 (&acc)[2][2][4][2], const Unit& u, int n, int wr, int wc, int fr, int fq) const {
;         EPI_OPAQUE
; #pragma unroll
;         for (int ai = 0; ai < 2; ++ai) {
;             u32x2 ga[4][2], gb[4][2];
; #pragma unroll
;             for (int m = 0; m < 4; ++m)
; #pragma unroll
;                 for (int bj = 0; bj < 2; ++bj) { const int row = u.pm * 256 + ai * 128 + wr * 64 + m * 16 + fr, col = u.pn * 256 + bj * 128 + wc * 32 + 8 * fq;
;                     const unsigned char* gp = (const unsigned char*)P + (size_t)row * ROWB + GATE_B0 + n * DM + col; ga[m][bj] = *(const u32x2*)gp; gb[m][bj] = *(const u32x2*)(gp + DM); }
; #pragma unroll
;             for (int m = 0; m < 4; ++m)
; #pragma unroll
;                 for (int bj = 0; bj < 2; ++bj) { const f32x4 a0 = un_unorm8(ga[m][bj].x), a1 = un_unorm8(ga[m][bj].y), b0 = un_unorm8(gb[m][bj].x), b1 = un_unorm8(gb[m][bj].y);
; #pragma unroll
;                     for (int j = 0; j < 4; ++j) { acc[ai][bj][m][0][j] *= a0[j] * __builtin_amdgcn_rcpf(b0[j]); acc[ai][bj][m][1][j] *= a1[j] * __builtin_amdgcn_rcpf(b1[j]); } }
.LBB0_617:
	s_andn2_b64 vcc, exec, s[4:5]
	s_cbranch_vccnz .LBB0_619
	s_and_b64 vcc, exec, s[46:47]
	s_cbranch_vccz .Lsm_a
	s_barrier
.Lsm_a:
	v_mov_b32_e32 v1, v180
	v_mov_b32_e32 v2, v181
	s_cmpk_eq_i32 s54, 0x800
	v_add_u32_e32 v1, s20, v1
	v_add_u32_e32 v154, s8, v1
	v_mov_b64_e32 v[148:149], s[68:69]
	s_cselect_b32 s56, 0, 0x800
	v_lshl_add_u32 v2, v2, 3, s42
	v_mad_i64_i32 v[150:151], s[4:5], v154, s33, v[148:149]
	v_ashrrev_i32_e32 v3, 31, v2
	v_lshl_add_u64 v[150:151], v[150:151], 0, s[56:57]
	v_lshl_add_u64 v[150:151], v[150:151], 0, v[2:3]
	v_lshl_add_u64 v[152:153], v[150:151], 0, s[64:65]
	v_add_co_u32_e32 v150, vcc, s12, v150
	global_load_dwordx2 v[184:185], v[152:153], off offset:2048
	s_nop 0
	v_addc_co_u32_e32 v151, vcc, 0, v151, vcc
	global_load_dwordx2 v[186:187], v[150:151], off
	global_load_dwordx2 v[208:209], v[152:153], off offset:2176
	global_load_dwordx2 v[210:211], v[152:153], off offset:128
	v_add_u32_e32 v150, 16, v154
	v_add_u32_e32 v156, 48, v154
	v_mad_i64_i32 v[150:151], s[4:5], v150, s33, v[148:149]
	v_mad_i64_i32 v[156:157], s[4:5], v156, s33, v[148:149]
	v_lshl_add_u64 v[150:151], v[150:151], 0, s[56:57]
	v_lshl_add_u64 v[156:157], v[156:157], 0, s[56:57]
	v_lshl_add_u64 v[150:151], v[150:151], 0, v[2:3]
	v_lshl_add_u64 v[152:153], v[156:157], 0, v[2:3]
	v_lshl_add_u64 v[156:157], v[150:151], 0, s[64:65]
	v_add_co_u32_e32 v150, vcc, s12, v150
	v_add_u32_e32 v155, 32, v154
	s_nop 0
	v_addc_co_u32_e32 v151, vcc, 0, v151, vcc
	global_load_dwordx2 v[176:177], v[156:157], off offset:2048
	global_load_dwordx2 v[178:179], v[150:151], off
	global_load_dwordx2 v[172:173], v[156:157], off offset:2176
	global_load_dwordx2 v[174:175], v[156:157], off offset:128
	v_mad_i64_i32 v[154:155], s[4:5], v155, s33, v[148:149]
	v_lshl_add_u64 v[154:155], v[154:155], 0, s[56:57]
	v_lshl_add_u64 v[154:155], v[154:155], 0, v[2:3]
	v_lshl_add_u64 v[160:161], v[154:155], 0, s[64:65]
	v_add_co_u32_e32 v154, vcc, s12, v154
	v_lshl_add_u64 v[212:213], v[152:153], 0, s[64:65]
	s_nop 0
	v_addc_co_u32_e32 v155, vcc, 0, v155, vcc
	global_load_dwordx2 v[168:169], v[160:161], off offset:2048
	global_load_dwordx2 v[170:171], v[154:155], off
	global_load_dwordx2 v[158:159], v[160:161], off offset:2176
	s_nop 0
	global_load_dwordx2 v[160:161], v[160:161], off offset:128
	v_add_co_u32_e32 v150, vcc, s12, v152
	v_add_u32_e32 v1, s43, v1
	s_nop 0
	v_addc_co_u32_e32 v151, vcc, 0, v153, vcc
	global_load_dwordx2 v[154:155], v[212:213], off offset:2048
	global_load_dwordx2 v[156:157], v[150:151], off
	s_nop 0
	global_load_dwordx2 v[150:151], v[212:213], off offset:2176
	global_load_dwordx2 v[152:153], v[212:213], off offset:128
	s_waitcnt vmcnt(0)
	v_cvt_f32_ubyte0_e32 v212, v184
	v_cvt_f32_ubyte1_e32 v213, v184
	v_cvt_f32_ubyte2_e32 v214, v184
	v_cvt_f32_ubyte0_e32 v219, v187
	v_cvt_f32_ubyte3_e32 v184, v184
	v_cvt_f32_ubyte3_e32 v218, v186
	v_max_f32_e32 v225, 0.5, v214
	v_max_f32_e32 v214, 0.5, v219
	v_max_f32_e32 v219, 0.5, v184
	v_cvt_f32_ubyte0_e32 v184, v185
	v_cvt_f32_ubyte2_e32 v217, v186
	v_cvt_f32_ubyte3_e32 v222, v187
	v_max_f32_e32 v224, 0.5, v213
	v_max_f32_e32 v213, 0.5, v218
	v_max_f32_e32 v218, 0.5, v184
	v_cvt_f32_ubyte1_e32 v184, v185
	v_max_f32_e32 v223, 0.5, v212
	v_max_f32_e32 v212, 0.5, v217
	v_max_f32_e32 v217, 0.5, v222
	v_max_f32_e32 v222, 0.5, v184
	v_cvt_f32_ubyte2_e32 v184, v185
	v_cvt_f32_ubyte0_e32 v215, v186
	v_cvt_f32_ubyte1_e32 v216, v186
	v_cvt_f32_ubyte1_e32 v220, v187
	v_cvt_f32_ubyte2_e32 v221, v187
	v_max_f32_e32 v226, 0.5, v184
	v_cvt_f32_ubyte3_e32 v184, v185
	v_max_f32_e32 v186, 0.5, v215
	v_max_f32_e32 v187, 0.5, v216
	v_max_f32_e32 v215, 0.5, v220
	v_max_f32_e32 v216, 0.5, v221
	v_max_f32_e32 v227, 0.5, v184
	v_rcp_f32_e32 v184, v223
	v_rcp_f32_e32 v185, v224
	v_rcp_f32_e32 v220, v225
	v_rcp_f32_e32 v221, v219
	v_rcp_f32_e32 v218, v218
	v_rcp_f32_e32 v219, v222
	v_rcp_f32_e32 v222, v226
	v_rcp_f32_e32 v223, v227
	v_pk_mul_f32 v[184:185], v[186:187], v[184:185]
	v_pk_mul_f32 v[186:187], v[212:213], v[220:221]
	v_pk_mul_f32 v[128:129], v[128:129], v[184:185]
	v_pk_mul_f32 v[130:131], v[130:131], v[186:187]
	v_pk_mul_f32 v[184:185], v[214:215], v[218:219]
	v_pk_mul_f32 v[186:187], v[216:217], v[222:223]
	v_cvt_f32_ubyte0_e32 v214, v208
	v_cvt_f32_ubyte1_e32 v215, v208
	v_cvt_f32_ubyte2_e32 v216, v208
	v_cvt_f32_ubyte3_e32 v208, v208
	v_max_f32_e32 v217, 0.5, v208
	v_cvt_f32_ubyte0_e32 v208, v209
	v_max_f32_e32 v218, 0.5, v208
	v_cvt_f32_ubyte1_e32 v208, v209
	v_max_f32_e32 v219, 0.5, v208
	v_cvt_f32_ubyte2_e32 v208, v209
	v_max_f32_e32 v214, 0.5, v214
	v_max_f32_e32 v215, 0.5, v215
	v_max_f32_e32 v216, 0.5, v216
	v_max_f32_e32 v220, 0.5, v208
	v_cvt_f32_ubyte3_e32 v208, v209
	v_max_f32_e32 v221, 0.5, v208
	v_rcp_f32_e32 v208, v214
	v_rcp_f32_e32 v209, v215
	v_rcp_f32_e32 v216, v216
	v_rcp_f32_e32 v217, v217
	v_pk_mul_f32 v[126:127], v[126:127], v[186:187]
	v_pk_mul_f32 v[124:125], v[124:125], v[184:185]
	v_cvt_f32_ubyte0_e32 v184, v210
	v_cvt_f32_ubyte1_e32 v185, v210
	v_cvt_f32_ubyte2_e32 v186, v210
	v_cvt_f32_ubyte3_e32 v187, v210
	v_cvt_f32_ubyte0_e32 v210, v211
	v_rcp_f32_e32 v214, v218
	v_rcp_f32_e32 v215, v219
	v_rcp_f32_e32 v218, v220
	v_rcp_f32_e32 v219, v221
	v_max_f32_e32 v212, 0.5, v210
	v_cvt_f32_ubyte1_e32 v210, v211
	v_max_f32_e32 v184, 0.5, v184
	v_max_f32_e32 v185, 0.5, v185
	v_max_f32_e32 v186, 0.5, v186
	v_max_f32_e32 v187, 0.5, v187
	v_max_f32_e32 v213, 0.5, v210
	v_cvt_f32_ubyte2_e32 v210, v211
	v_cvt_f32_ubyte3_e32 v211, v211
	v_max_f32_e32 v210, 0.5, v210
	v_max_f32_e32 v211, 0.5, v211
	v_pk_mul_f32 v[184:185], v[184:185], v[208:209]
	v_pk_mul_f32 v[186:187], v[186:187], v[216:217]
; __device__ __forceinline__ f32x4 un_unorm8(unsigned w) { return (f32x4){fmaxf((float)(w & 255u), 0.5f), fmaxf((float)((w >> 8) & 255u), 0.5f), fmaxf((float)((w >> 16) & 255u), 0.5f), fmaxf((float)(w >> 24), 0.5f)}; }
;     __device__ __forceinline__ void seam(f32x4 (&acc)[2][2][4][2], const Unit& u, int n, int wr, int wc, int fr, int fq) const {
;     ...
;             for (int m = 0; m < 4; ++m)
; #pragma unroll
;                 for (int bj = 0; bj < 2; ++bj) { const f32x4 a0 = un_unorm8(ga[m][bj].x), a1 = un_unorm8(ga[m][bj].y), b0 = un_unorm8(gb[m][bj].x), b1 = un_unorm8(gb[m][bj].y);
; #pragma unroll
;                     for (int j = 0; j < 4; ++j) { acc[ai][bj][m][0][j] *= a0[j] * __builtin_amdgcn_rcpf(b0[j]); acc[ai][bj][m][1][j] *= a1[j] * __builtin_amdgcn_rcpf(b1[j]); } }
	v_pk_mul_f32 v[120:121], v[120:121], v[184:185]
	v_pk_mul_f32 v[122:123], v[122:123], v[186:187]
	v_pk_mul_f32 v[184:185], v[212:213], v[214:215]
	v_pk_mul_f32 v[186:187], v[210:211], v[218:219]
	v_cvt_f32_ubyte0_e32 v210, v176
	v_cvt_f32_ubyte1_e32 v211, v176
	v_cvt_f32_ubyte2_e32 v212, v176
	v_cvt_f32_ubyte3_e32 v176, v176
	v_max_f32_e32 v213, 0.5, v176
	v_cvt_f32_ubyte0_e32 v176, v177
	v_max_f32_e32 v214, 0.5, v176
	v_cvt_f32_ubyte1_e32 v176, v177
	v_max_f32_e32 v215, 0.5, v176
	v_cvt_f32_ubyte2_e32 v176, v177
	v_max_f32_e32 v210, 0.5, v210
	v_max_f32_e32 v211, 0.5, v211
	v_max_f32_e32 v216, 0.5, v176
	v_cvt_f32_ubyte3_e32 v176, v177
	v_max_f32_e32 v212, 0.5, v212
	v_max_f32_e32 v217, 0.5, v176
	v_rcp_f32_e32 v176, v210
	v_rcp_f32_e32 v177, v211
	v_pk_mul_f32 v[118:119], v[118:119], v[186:187]
	v_pk_mul_f32 v[116:117], v[116:117], v[184:185]
	v_cvt_f32_ubyte0_e32 v184, v178
	v_cvt_f32_ubyte1_e32 v185, v178
	v_cvt_f32_ubyte2_e32 v186, v178
	v_cvt_f32_ubyte3_e32 v178, v178
	v_rcp_f32_e32 v210, v214
	v_rcp_f32_e32 v212, v212
	v_rcp_f32_e32 v213, v213
	v_rcp_f32_e32 v211, v215
	v_max_f32_e32 v187, 0.5, v178
	v_cvt_f32_ubyte0_e32 v178, v179
	v_max_f32_e32 v184, 0.5, v184
	v_max_f32_e32 v185, 0.5, v185
	v_max_f32_e32 v208, 0.5, v178
	v_cvt_f32_ubyte1_e32 v178, v179
	v_max_f32_e32 v186, 0.5, v186
	v_max_f32_e32 v209, 0.5, v178
	v_pk_mul_f32 v[176:177], v[184:185], v[176:177]
	v_pk_mul_f32 v[184:185], v[186:187], v[212:213]
	v_pk_mul_f32 v[112:113], v[112:113], v[176:177]
	v_pk_mul_f32 v[176:177], v[208:209], v[210:211]
	v_cvt_f32_ubyte0_e32 v186, v172
	v_cvt_f32_ubyte1_e32 v187, v172
	v_cvt_f32_ubyte2_e32 v208, v172
	v_cvt_f32_ubyte3_e32 v172, v172
	v_rcp_f32_e32 v214, v216
	v_rcp_f32_e32 v215, v217
	v_max_f32_e32 v209, 0.5, v172
	v_cvt_f32_ubyte0_e32 v172, v173
	v_max_f32_e32 v210, 0.5, v172
	v_cvt_f32_ubyte1_e32 v172, v173
	v_cvt_f32_ubyte2_e32 v178, v179
	v_cvt_f32_ubyte3_e32 v179, v179
	v_max_f32_e32 v211, 0.5, v172
	v_cvt_f32_ubyte2_e32 v172, v173
	v_max_f32_e32 v178, 0.5, v178
	v_max_f32_e32 v179, 0.5, v179
	v_max_f32_e32 v186, 0.5, v186
	v_max_f32_e32 v187, 0.5, v187
	v_max_f32_e32 v212, 0.5, v172
	v_cvt_f32_ubyte3_e32 v172, v173
	v_pk_mul_f32 v[178:179], v[178:179], v[214:215]
	v_max_f32_e32 v208, 0.5, v208
	v_max_f32_e32 v213, 0.5, v172
	v_rcp_f32_e32 v172, v186
	v_rcp_f32_e32 v173, v187
	v_pk_mul_f32 v[110:111], v[110:111], v[178:179]
	v_pk_mul_f32 v[108:109], v[108:109], v[176:177]
	v_cvt_f32_ubyte0_e32 v176, v174
	v_cvt_f32_ubyte1_e32 v177, v174
	v_cvt_f32_ubyte2_e32 v178, v174
	v_cvt_f32_ubyte3_e32 v174, v174
	v_rcp_f32_e32 v186, v210
	v_rcp_f32_e32 v208, v208
	v_rcp_f32_e32 v209, v209
	v_rcp_f32_e32 v187, v211
	v_max_f32_e32 v179, 0.5, v174
	v_cvt_f32_ubyte0_e32 v174, v175
	v_pk_mul_f32 v[114:115], v[114:115], v[184:185]
	v_max_f32_e32 v176, 0.5, v176
	v_max_f32_e32 v177, 0.5, v177
	v_max_f32_e32 v184, 0.5, v174
	v_cvt_f32_ubyte1_e32 v174, v175
	v_max_f32_e32 v178, 0.5, v178
	v_max_f32_e32 v185, 0.5, v174
	v_pk_mul_f32 v[172:173], v[176:177], v[172:173]
	v_pk_mul_f32 v[176:177], v[178:179], v[208:209]
	v_pk_mul_f32 v[104:105], v[104:105], v[172:173]
	v_pk_mul_f32 v[172:173], v[184:185], v[186:187]
	v_cvt_f32_ubyte0_e32 v178, v168
	v_cvt_f32_ubyte1_e32 v179, v168
	v_cvt_f32_ubyte2_e32 v184, v168
	v_cvt_f32_ubyte3_e32 v168, v168
	v_rcp_f32_e32 v210, v212
	v_rcp_f32_e32 v211, v213
	v_max_f32_e32 v185, 0.5, v168
	v_cvt_f32_ubyte0_e32 v168, v169
	v_max_f32_e32 v186, 0.5, v168
	v_cvt_f32_ubyte1_e32 v168, v169
	v_cvt_f32_ubyte2_e32 v174, v175
	v_cvt_f32_ubyte3_e32 v175, v175
	v_max_f32_e32 v187, 0.5, v168
	v_cvt_f32_ubyte2_e32 v168, v169
	v_max_f32_e32 v174, 0.5, v174
	v_max_f32_e32 v175, 0.5, v175
	v_max_f32_e32 v178, 0.5, v178
	v_max_f32_e32 v179, 0.5, v179
	v_max_f32_e32 v208, 0.5, v168
	v_cvt_f32_ubyte3_e32 v168, v169
	v_pk_mul_f32 v[174:175], v[174:175], v[210:211]
	v_max_f32_e32 v184, 0.5, v184
	v_max_f32_e32 v209, 0.5, v168
	v_rcp_f32_e32 v168, v178
	v_rcp_f32_e32 v169, v179
	v_pk_mul_f32 v[102:103], v[102:103], v[174:175]
	v_pk_mul_f32 v[100:101], v[100:101], v[172:173]
	v_cvt_f32_ubyte0_e32 v172, v170
	v_cvt_f32_ubyte1_e32 v173, v170
	v_cvt_f32_ubyte2_e32 v174, v170
	v_cvt_f32_ubyte3_e32 v170, v170
	v_rcp_f32_e32 v178, v186
	v_rcp_f32_e32 v184, v184
	v_rcp_f32_e32 v185, v185
	v_rcp_f32_e32 v179, v187
	v_max_f32_e32 v175, 0.5, v170
	v_cvt_f32_ubyte0_e32 v170, v171
	v_pk_mul_f32 v[106:107], v[106:107], v[176:177]
	v_max_f32_e32 v172, 0.5, v172
	v_max_f32_e32 v173, 0.5, v173
	v_max_f32_e32 v176, 0.5, v170
	v_cvt_f32_ubyte1_e32 v170, v171
	v_max_f32_e32 v174, 0.5, v174
	v_max_f32_e32 v177, 0.5, v170
	v_pk_mul_f32 v[168:169], v[172:173], v[168:169]
	v_pk_mul_f32 v[172:173], v[174:175], v[184:185]
	v_pk_mul_f32 v[96:97], v[96:97], v[168:169]
	v_pk_mul_f32 v[168:169], v[176:177], v[178:179]
	v_cvt_f32_ubyte0_e32 v174, v158
	v_cvt_f32_ubyte1_e32 v175, v158
	v_cvt_f32_ubyte2_e32 v176, v158
	v_cvt_f32_ubyte3_e32 v158, v158
	v_rcp_f32_e32 v186, v208
	v_rcp_f32_e32 v187, v209
	v_max_f32_e32 v177, 0.5, v158
	v_cvt_f32_ubyte0_e32 v158, v159
	v_max_f32_e32 v178, 0.5, v158
	v_cvt_f32_ubyte1_e32 v158, v159
	v_cvt_f32_ubyte2_e32 v170, v171
	v_cvt_f32_ubyte3_e32 v171, v171
	v_max_f32_e32 v179, 0.5, v158
	v_cvt_f32_ubyte2_e32 v158, v159
	v_max_f32_e32 v170, 0.5, v170
	v_max_f32_e32 v171, 0.5, v171
	v_max_f32_e32 v174, 0.5, v174
	v_max_f32_e32 v175, 0.5, v175
	v_max_f32_e32 v184, 0.5, v158
	v_cvt_f32_ubyte3_e32 v158, v159
	v_pk_mul_f32 v[170:171], v[170:171], v[186:187]
	v_max_f32_e32 v176, 0.5, v176
	v_max_f32_e32 v185, 0.5, v158
	v_rcp_f32_e32 v158, v174
	v_rcp_f32_e32 v159, v175
	v_pk_mul_f32 v[94:95], v[94:95], v[170:171]
; __device__ __forceinline__ f32x4 un_unorm8(unsigned w) { return (f32x4){fmaxf((float)(w & 255u), 0.5f), fmaxf((float)((w >> 8) & 255u), 0.5f), fmaxf((float)((w >> 16) & 255u), 0.5f), fmaxf((float)(w >> 24), 0.5f)}; }
;     __device__ __forceinline__ void seam(f32x4 (&acc)[2][2][4][2], const Unit& u, int n, int wr, int wc, int fr, int fq) const {
;     ...
;                 for (int bj = 0; bj < 2; ++bj) { const int row = u.pm * 256 + ai * 128 + wr * 64 + m * 16 + fr, col = u.pn * 256 + bj * 128 + wc * 32 + 8 * fq;
;                     const unsigned char* gp = (const unsigned char*)P + (size_t)row * ROWB + GATE_B0 + n * DM + col; ga[m][bj] = *(const u32x2*)gp; gb[m][bj] = *(const u32x2*)(gp + DM); }
; #pragma unroll
;             for (int m = 0; m < 4; ++m)
; #pragma unroll
;                 for (int bj = 0; bj < 2; ++bj) { const f32x4 a0 = un_unorm8(ga[m][bj].x), a1 = un_unorm8(ga[m][bj].y), b0 = un_unorm8(gb[m][bj].x), b1 = un_unorm8(gb[m][bj].y);
; #pragma unroll
;                     for (int j = 0; j < 4; ++j) { acc[ai][bj][m][0][j] *= a0[j] * __builtin_amdgcn_rcpf(b0[j]); acc[ai][bj][m][1][j] *= a1[j] * __builtin_amdgcn_rcpf(b1[j]); } }
	v_pk_mul_f32 v[92:93], v[92:93], v[168:169]
	v_cvt_f32_ubyte0_e32 v168, v160
	v_cvt_f32_ubyte1_e32 v169, v160
	v_cvt_f32_ubyte2_e32 v170, v160
	v_cvt_f32_ubyte3_e32 v160, v160
	v_rcp_f32_e32 v174, v178
	v_rcp_f32_e32 v176, v176
	v_rcp_f32_e32 v177, v177
	v_rcp_f32_e32 v175, v179
	v_max_f32_e32 v171, 0.5, v160
	v_cvt_f32_ubyte0_e32 v160, v161
	v_pk_mul_f32 v[98:99], v[98:99], v[172:173]
	v_max_f32_e32 v168, 0.5, v168
	v_max_f32_e32 v169, 0.5, v169
	v_max_f32_e32 v172, 0.5, v160
	v_cvt_f32_ubyte1_e32 v160, v161
	v_max_f32_e32 v170, 0.5, v170
	v_max_f32_e32 v173, 0.5, v160
	v_pk_mul_f32 v[158:159], v[168:169], v[158:159]
	v_pk_mul_f32 v[168:169], v[170:171], v[176:177]
	v_pk_mul_f32 v[88:89], v[88:89], v[158:159]
	v_pk_mul_f32 v[158:159], v[172:173], v[174:175]
	v_cvt_f32_ubyte0_e32 v170, v154
	v_cvt_f32_ubyte1_e32 v171, v154
	v_cvt_f32_ubyte2_e32 v172, v154
	v_cvt_f32_ubyte3_e32 v154, v154
	v_max_f32_e32 v173, 0.5, v154
	v_cvt_f32_ubyte0_e32 v154, v155
	v_rcp_f32_e32 v178, v184
	v_rcp_f32_e32 v179, v185
	v_max_f32_e32 v174, 0.5, v154
	v_cvt_f32_ubyte1_e32 v154, v155
	v_max_f32_e32 v175, 0.5, v154
	v_cvt_f32_ubyte2_e32 v154, v155
	v_cvt_f32_ubyte2_e32 v160, v161
	v_cvt_f32_ubyte3_e32 v161, v161
	v_max_f32_e32 v170, 0.5, v170
	v_max_f32_e32 v171, 0.5, v171
	v_max_f32_e32 v172, 0.5, v172
	v_max_f32_e32 v176, 0.5, v154
	v_cvt_f32_ubyte3_e32 v154, v155
	v_max_f32_e32 v160, 0.5, v160
	v_max_f32_e32 v161, 0.5, v161
	v_max_f32_e32 v177, 0.5, v154
	v_rcp_f32_e32 v154, v170
	v_rcp_f32_e32 v155, v171
	v_rcp_f32_e32 v172, v172
	v_rcp_f32_e32 v173, v173
	v_pk_mul_f32 v[160:161], v[160:161], v[178:179]
	v_pk_mul_f32 v[84:85], v[84:85], v[158:159]
	v_pk_mul_f32 v[86:87], v[86:87], v[160:161]
	v_cvt_f32_ubyte0_e32 v158, v156
	v_cvt_f32_ubyte1_e32 v159, v156
	v_cvt_f32_ubyte2_e32 v160, v156
	v_cvt_f32_ubyte3_e32 v156, v156
	v_max_f32_e32 v158, 0.5, v158
	v_max_f32_e32 v159, 0.5, v159
	v_max_f32_e32 v160, 0.5, v160
	v_max_f32_e32 v161, 0.5, v156
	v_rcp_f32_e32 v170, v174
	v_rcp_f32_e32 v171, v175
	v_cvt_f32_ubyte0_e32 v156, v157
	v_pk_mul_f32 v[154:155], v[158:159], v[154:155]
	v_pk_mul_f32 v[158:159], v[160:161], v[172:173]
	v_mad_i64_i32 v[160:161], s[4:5], v1, s33, v[148:149]
	v_pk_mul_f32 v[90:91], v[90:91], v[168:169]
	v_max_f32_e32 v168, 0.5, v156
	v_cvt_f32_ubyte1_e32 v156, v157
	v_lshl_add_u64 v[160:161], v[160:161], 0, s[56:57]
	v_max_f32_e32 v169, 0.5, v156
	v_lshl_add_u64 v[160:161], v[160:161], 0, v[2:3]
	v_pk_mul_f32 v[80:81], v[80:81], v[154:155]
	v_pk_mul_f32 v[154:155], v[168:169], v[170:171]
	v_add_co_u32_e32 v168, vcc, s12, v160
	v_rcp_f32_e32 v174, v176
	s_nop 0
	v_addc_co_u32_e32 v169, vcc, 0, v161, vcc
	global_load_dwordx2 v[172:173], v[168:169], off
	v_rcp_f32_e32 v175, v177
	v_cvt_f32_ubyte2_e32 v156, v157
	v_cvt_f32_ubyte3_e32 v157, v157
	v_max_f32_e32 v156, 0.5, v156
	v_max_f32_e32 v157, 0.5, v157
	v_lshl_add_u64 v[160:161], v[160:161], 0, s[64:65]
	v_pk_mul_f32 v[156:157], v[156:157], v[174:175]
	global_load_dwordx2 v[174:175], v[160:161], off offset:2048
	v_cvt_f32_ubyte0_e32 v168, v150
	v_cvt_f32_ubyte1_e32 v169, v150
	v_cvt_f32_ubyte2_e32 v170, v150
	v_cvt_f32_ubyte3_e32 v150, v150
	v_max_f32_e32 v171, 0.5, v150
	v_cvt_f32_ubyte0_e32 v150, v151
	v_max_f32_e32 v176, 0.5, v150
	v_cvt_f32_ubyte1_e32 v150, v151
	v_max_f32_e32 v177, 0.5, v150
	v_cvt_f32_ubyte2_e32 v150, v151
	v_max_f32_e32 v178, 0.5, v150
	v_cvt_f32_ubyte3_e32 v150, v151
	v_pk_mul_f32 v[78:79], v[78:79], v[156:157]
	v_pk_mul_f32 v[76:77], v[76:77], v[154:155]
	v_cvt_f32_ubyte0_e32 v154, v152
	v_cvt_f32_ubyte1_e32 v155, v152
	v_cvt_f32_ubyte2_e32 v156, v152
	v_cvt_f32_ubyte3_e32 v152, v152
	v_max_f32_e32 v168, 0.5, v168
	v_max_f32_e32 v169, 0.5, v169
	v_max_f32_e32 v179, 0.5, v150
	v_max_f32_e32 v157, 0.5, v152
	v_cvt_f32_ubyte0_e32 v152, v153
	v_rcp_f32_e32 v150, v168
	v_rcp_f32_e32 v168, v176
	v_rcp_f32_e32 v151, v169
	v_rcp_f32_e32 v169, v177
	v_rcp_f32_e32 v176, v178
	v_rcp_f32_e32 v177, v179
	v_pk_mul_f32 v[82:83], v[82:83], v[158:159]
	v_max_f32_e32 v158, 0.5, v152
	v_cvt_f32_ubyte1_e32 v152, v153
	v_max_f32_e32 v159, 0.5, v152
	v_cvt_f32_ubyte2_e32 v152, v153
	v_cvt_f32_ubyte3_e32 v153, v153
	v_max_f32_e32 v152, 0.5, v152
	v_max_f32_e32 v153, 0.5, v153
	v_pk_mul_f32 v[152:153], v[152:153], v[176:177]
	global_load_dwordx2 v[176:177], v[160:161], off offset:2176
	global_load_dwordx2 v[178:179], v[160:161], off offset:128
	v_max_f32_e32 v154, 0.5, v154
	v_max_f32_e32 v155, 0.5, v155
	v_pk_mul_f32 v[150:151], v[154:155], v[150:151]
	v_max_f32_e32 v170, 0.5, v170
	v_pk_mul_f32 v[72:73], v[72:73], v[150:151]
	v_pk_mul_f32 v[150:151], v[158:159], v[168:169]
	v_rcp_f32_e32 v170, v170
	v_pk_mul_f32 v[68:69], v[68:69], v[150:151]
	v_add_u32_e32 v150, 16, v1
	v_mad_i64_i32 v[150:151], s[4:5], v150, s33, v[148:149]
	v_rcp_f32_e32 v171, v171
	v_lshl_add_u64 v[150:151], v[150:151], 0, s[56:57]
	v_lshl_add_u64 v[150:151], v[150:151], 0, v[2:3]
	v_pk_mul_f32 v[70:71], v[70:71], v[152:153]
	v_lshl_add_u64 v[152:153], v[150:151], 0, s[64:65]
	v_add_co_u32_e32 v150, vcc, s12, v150
	v_max_f32_e32 v156, 0.5, v156
	s_nop 0
	v_addc_co_u32_e32 v151, vcc, 0, v151, vcc
	v_pk_mul_f32 v[154:155], v[156:157], v[170:171]
	global_load_dwordx2 v[184:185], v[150:151], off
	global_load_dwordx2 v[186:187], v[152:153], off offset:2048
	global_load_dwordx2 v[168:169], v[152:153], off offset:2176
	global_load_dwordx2 v[170:171], v[152:153], off offset:128
	v_add_u32_e32 v150, 32, v1
	v_mad_i64_i32 v[150:151], s[4:5], v150, s33, v[148:149]
	v_lshl_add_u64 v[150:151], v[150:151], 0, s[56:57]
	v_lshl_add_u64 v[150:151], v[150:151], 0, v[2:3]
	v_lshl_add_u64 v[152:153], v[150:151], 0, s[64:65]
	v_add_co_u32_e32 v150, vcc, s12, v150
	v_pk_mul_f32 v[74:75], v[74:75], v[154:155]
	s_nop 0
	v_addc_co_u32_e32 v151, vcc, 0, v151, vcc
	global_load_dwordx2 v[160:161], v[150:151], off
	global_load_dwordx2 v[158:159], v[152:153], off offset:2048
	global_load_dwordx2 v[154:155], v[152:153], off offset:2176
	global_load_dwordx2 v[156:157], v[152:153], off offset:128
	v_add_u32_e32 v1, 48, v1
	v_mad_i64_i32 v[148:149], s[4:5], v1, s33, v[148:149]
	s_waitcnt vmcnt(0)
; __device__ __forceinline__ f32x4 un_unorm8(unsigned w) { return (f32x4){fmaxf((float)(w & 255u), 0.5f), fmaxf((float)((w >> 8) & 255u), 0.5f), fmaxf((float)((w >> 16) & 255u), 0.5f), fmaxf((float)(w >> 24), 0.5f)}; }
;     __device__ __forceinline__ void seam(f32x4 (&acc)[2][2][4][2], const Unit& u, int n, int wr, int wc, int fr, int fq) const {
;     ...
;             for (int m = 0; m < 4; ++m)
; #pragma unroll
;                 for (int bj = 0; bj < 2; ++bj) { const f32x4 a0 = un_unorm8(ga[m][bj].x), a1 = un_unorm8(ga[m][bj].y), b0 = un_unorm8(gb[m][bj].x), b1 = un_unorm8(gb[m][bj].y);
; #pragma unroll
;                     for (int j = 0; j < 4; ++j) { acc[ai][bj][m][0][j] *= a0[j] * __builtin_amdgcn_rcpf(b0[j]); acc[ai][bj][m][1][j] *= a1[j] * __builtin_amdgcn_rcpf(b1[j]); } }
	v_cvt_f32_ubyte0_e32 v1, v172
	v_max_f32_e32 v208, 0.5, v1
	v_cvt_f32_ubyte1_e32 v1, v172
	v_max_f32_e32 v209, 0.5, v1
	v_cvt_f32_ubyte2_e32 v1, v172
	v_max_f32_e32 v210, 0.5, v1
	v_cvt_f32_ubyte3_e32 v1, v172
	v_max_f32_e32 v211, 0.5, v1
	v_cvt_f32_ubyte0_e32 v1, v173
	v_max_f32_e32 v212, 0.5, v1
	v_cvt_f32_ubyte1_e32 v1, v173
	v_max_f32_e32 v213, 0.5, v1
	v_cvt_f32_ubyte2_e32 v1, v173
	v_max_f32_e32 v172, 0.5, v1
	v_cvt_f32_ubyte3_e32 v1, v173
	v_cvt_f32_ubyte1_e32 v214, v174
	v_max_f32_e32 v173, 0.5, v1
	v_cvt_f32_ubyte0_e32 v1, v174
	v_max_f32_e32 v215, 0.5, v214
	v_cvt_f32_ubyte2_e32 v214, v174
	v_cvt_f32_ubyte3_e32 v174, v174
	v_max_f32_e32 v217, 0.5, v174
	v_cvt_f32_ubyte0_e32 v174, v175
	v_max_f32_e32 v216, 0.5, v214
	v_max_f32_e32 v214, 0.5, v174
	v_cvt_f32_ubyte1_e32 v174, v175
	v_max_f32_e32 v218, 0.5, v174
	v_cvt_f32_ubyte2_e32 v174, v175
	v_max_f32_e32 v219, 0.5, v174
	v_cvt_f32_ubyte3_e32 v174, v175
	v_max_f32_e32 v220, 0.5, v174
	v_max_f32_e32 v1, 0.5, v1
	v_rcp_f32_e32 v175, v215
	v_rcp_f32_e32 v215, v218
	v_rcp_f32_e32 v218, v219
	v_rcp_f32_e32 v219, v220
	v_rcp_f32_e32 v174, v1
	v_rcp_f32_e32 v214, v214
	v_rcp_f32_e32 v216, v216
	v_rcp_f32_e32 v217, v217
	v_pk_mul_f32 v[172:173], v[172:173], v[218:219]
	v_cvt_f32_ubyte0_e32 v1, v178
	v_pk_mul_f32 v[174:175], v[208:209], v[174:175]
	v_pk_mul_f32 v[62:63], v[62:63], v[172:173]
	v_max_f32_e32 v172, 0.5, v1
	v_cvt_f32_ubyte1_e32 v1, v178
	v_pk_mul_f32 v[64:65], v[64:65], v[174:175]
	v_pk_mul_f32 v[174:175], v[212:213], v[214:215]
	v_max_f32_e32 v173, 0.5, v1
	v_cvt_f32_ubyte2_e32 v1, v178
	v_pk_mul_f32 v[60:61], v[60:61], v[174:175]
	v_max_f32_e32 v174, 0.5, v1
	v_cvt_f32_ubyte3_e32 v1, v178
	v_pk_mul_f32 v[208:209], v[210:211], v[216:217]
	v_max_f32_e32 v175, 0.5, v1
	v_cvt_f32_ubyte0_e32 v1, v179
	v_pk_mul_f32 v[66:67], v[66:67], v[208:209]
	v_max_f32_e32 v208, 0.5, v1
	v_cvt_f32_ubyte1_e32 v1, v179
	v_max_f32_e32 v209, 0.5, v1
	v_cvt_f32_ubyte2_e32 v1, v179
	v_max_f32_e32 v178, 0.5, v1
	v_cvt_f32_ubyte3_e32 v1, v179
	v_cvt_f32_ubyte1_e32 v210, v176
	v_max_f32_e32 v179, 0.5, v1
	v_cvt_f32_ubyte0_e32 v1, v176
	v_max_f32_e32 v211, 0.5, v210
	v_cvt_f32_ubyte2_e32 v210, v176
	v_cvt_f32_ubyte3_e32 v176, v176
	v_lshl_add_u64 v[148:149], v[148:149], 0, s[56:57]
	v_max_f32_e32 v213, 0.5, v176
	v_cvt_f32_ubyte0_e32 v176, v177
	v_lshl_add_u64 v[2:3], v[148:149], 0, v[2:3]
	v_max_f32_e32 v212, 0.5, v210
	v_max_f32_e32 v210, 0.5, v176
	v_cvt_f32_ubyte1_e32 v176, v177
	v_lshl_add_u64 v[148:149], v[2:3], 0, s[64:65]
	v_add_co_u32_e32 v2, vcc, s12, v2
	v_max_f32_e32 v214, 0.5, v176
	v_cvt_f32_ubyte2_e32 v176, v177
	v_addc_co_u32_e32 v3, vcc, 0, v3, vcc
	v_max_f32_e32 v1, 0.5, v1
	v_max_f32_e32 v215, 0.5, v176
	v_cvt_f32_ubyte3_e32 v176, v177
	global_load_dwordx2 v[152:153], v[2:3], off
	global_load_dwordx2 v[150:151], v[148:149], off offset:2048
	s_nop 0
	global_load_dwordx2 v[2:3], v[148:149], off offset:2176
	s_nop 0
	global_load_dwordx2 v[148:149], v[148:149], off offset:128
	v_max_f32_e32 v216, 0.5, v176
	v_rcp_f32_e32 v176, v1
	v_rcp_f32_e32 v177, v211
	v_rcp_f32_e32 v210, v210
	v_rcp_f32_e32 v211, v214
	v_rcp_f32_e32 v212, v212
	v_rcp_f32_e32 v213, v213
	v_rcp_f32_e32 v214, v215
	v_rcp_f32_e32 v215, v216
	v_pk_mul_f32 v[172:173], v[172:173], v[176:177]
	v_cvt_f32_ubyte0_e32 v1, v184
	v_pk_mul_f32 v[56:57], v[56:57], v[172:173]
	v_pk_mul_f32 v[172:173], v[208:209], v[210:211]
	v_pk_mul_f32 v[174:175], v[174:175], v[212:213]
	v_pk_mul_f32 v[52:53], v[52:53], v[172:173]
	v_max_f32_e32 v172, 0.5, v1
	v_cvt_f32_ubyte1_e32 v1, v184
	v_pk_mul_f32 v[58:59], v[58:59], v[174:175]
	v_pk_mul_f32 v[174:175], v[178:179], v[214:215]
	v_max_f32_e32 v173, 0.5, v1
	v_cvt_f32_ubyte2_e32 v1, v184
	v_pk_mul_f32 v[54:55], v[54:55], v[174:175]
	v_max_f32_e32 v174, 0.5, v1
	v_cvt_f32_ubyte3_e32 v1, v184
	v_max_f32_e32 v175, 0.5, v1
	v_cvt_f32_ubyte0_e32 v1, v185
	v_max_f32_e32 v176, 0.5, v1
	v_cvt_f32_ubyte1_e32 v1, v185
	v_max_f32_e32 v177, 0.5, v1
	v_cvt_f32_ubyte2_e32 v1, v185
	v_cvt_f32_ubyte1_e32 v184, v186
	v_max_f32_e32 v178, 0.5, v1
	v_cvt_f32_ubyte3_e32 v1, v185
	v_max_f32_e32 v185, 0.5, v184
	v_cvt_f32_ubyte2_e32 v184, v186
	v_max_f32_e32 v208, 0.5, v184
	v_cvt_f32_ubyte3_e32 v184, v186
	v_max_f32_e32 v209, 0.5, v184
	v_cvt_f32_ubyte0_e32 v184, v187
	v_max_f32_e32 v179, 0.5, v1
	v_cvt_f32_ubyte0_e32 v1, v186
	v_max_f32_e32 v186, 0.5, v184
	v_cvt_f32_ubyte1_e32 v184, v187
	v_max_f32_e32 v210, 0.5, v184
	v_cvt_f32_ubyte2_e32 v184, v187
	v_max_f32_e32 v1, 0.5, v1
	v_max_f32_e32 v211, 0.5, v184
	v_cvt_f32_ubyte3_e32 v184, v187
	v_max_f32_e32 v212, 0.5, v184
	v_rcp_f32_e32 v184, v1
	v_rcp_f32_e32 v185, v185
	v_rcp_f32_e32 v186, v186
	v_rcp_f32_e32 v187, v210
	v_rcp_f32_e32 v208, v208
	v_rcp_f32_e32 v209, v209
	v_rcp_f32_e32 v210, v211
	v_rcp_f32_e32 v211, v212
	v_pk_mul_f32 v[172:173], v[172:173], v[184:185]
	v_cvt_f32_ubyte0_e32 v1, v170
	v_pk_mul_f32 v[48:49], v[48:49], v[172:173]
	v_pk_mul_f32 v[172:173], v[176:177], v[186:187]
	v_pk_mul_f32 v[174:175], v[174:175], v[208:209]
	v_pk_mul_f32 v[44:45], v[44:45], v[172:173]
	v_max_f32_e32 v172, 0.5, v1
	v_cvt_f32_ubyte1_e32 v1, v170
	v_pk_mul_f32 v[50:51], v[50:51], v[174:175]
	v_pk_mul_f32 v[174:175], v[178:179], v[210:211]
	v_max_f32_e32 v173, 0.5, v1
	v_cvt_f32_ubyte2_e32 v1, v170
	v_pk_mul_f32 v[46:47], v[46:47], v[174:175]
	v_max_f32_e32 v174, 0.5, v1
	v_cvt_f32_ubyte3_e32 v1, v170
	v_max_f32_e32 v175, 0.5, v1
	v_cvt_f32_ubyte0_e32 v1, v171
	v_max_f32_e32 v176, 0.5, v1
	v_cvt_f32_ubyte1_e32 v1, v171
	v_max_f32_e32 v177, 0.5, v1
	v_cvt_f32_ubyte2_e32 v1, v171
	v_max_f32_e32 v170, 0.5, v1
	v_cvt_f32_ubyte3_e32 v1, v171
	v_cvt_f32_ubyte1_e32 v178, v168
; __device__ __forceinline__ f32x4 un_unorm8(unsigned w) { return (f32x4){fmaxf((float)(w & 255u), 0.5f), fmaxf((float)((w >> 8) & 255u), 0.5f), fmaxf((float)((w >> 16) & 255u), 0.5f), fmaxf((float)(w >> 24), 0.5f)}; }
;     __device__ __forceinline__ void seam(f32x4 (&acc)[2][2][4][2], const Unit& u, int n, int wr, int wc, int fr, int fq) const {
;     ...
;             for (int m = 0; m < 4; ++m)
; #pragma unroll
;                 for (int bj = 0; bj < 2; ++bj) { const f32x4 a0 = un_unorm8(ga[m][bj].x), a1 = un_unorm8(ga[m][bj].y), b0 = un_unorm8(gb[m][bj].x), b1 = un_unorm8(gb[m][bj].y);
; #pragma unroll
;                     for (int j = 0; j < 4; ++j) { acc[ai][bj][m][0][j] *= a0[j] * __builtin_amdgcn_rcpf(b0[j]); acc[ai][bj][m][1][j] *= a1[j] * __builtin_amdgcn_rcpf(b1[j]); } }
	v_max_f32_e32 v171, 0.5, v1
	v_cvt_f32_ubyte0_e32 v1, v168
	v_max_f32_e32 v179, 0.5, v178
	v_cvt_f32_ubyte2_e32 v178, v168
	v_cvt_f32_ubyte3_e32 v168, v168
	v_max_f32_e32 v185, 0.5, v168
	v_cvt_f32_ubyte0_e32 v168, v169
	v_max_f32_e32 v184, 0.5, v178
	v_max_f32_e32 v178, 0.5, v168
	v_cvt_f32_ubyte1_e32 v168, v169
	v_max_f32_e32 v186, 0.5, v168
	v_cvt_f32_ubyte2_e32 v168, v169
	v_max_f32_e32 v1, 0.5, v1
	v_max_f32_e32 v187, 0.5, v168
	v_cvt_f32_ubyte3_e32 v168, v169
	v_max_f32_e32 v208, 0.5, v168
	v_rcp_f32_e32 v168, v1
	v_rcp_f32_e32 v169, v179
	v_rcp_f32_e32 v178, v178
	v_rcp_f32_e32 v179, v186
	v_rcp_f32_e32 v186, v187
	v_rcp_f32_e32 v187, v208
	v_pk_mul_f32 v[168:169], v[172:173], v[168:169]
	v_rcp_f32_e32 v184, v184
	v_rcp_f32_e32 v185, v185
	v_pk_mul_f32 v[40:41], v[40:41], v[168:169]
	v_pk_mul_f32 v[168:169], v[176:177], v[178:179]
	v_cvt_f32_ubyte0_e32 v1, v160
	v_pk_mul_f32 v[36:37], v[36:37], v[168:169]
	v_max_f32_e32 v168, 0.5, v1
	v_cvt_f32_ubyte1_e32 v1, v160
	v_pk_mul_f32 v[170:171], v[170:171], v[186:187]
	v_max_f32_e32 v169, 0.5, v1
	v_cvt_f32_ubyte2_e32 v1, v160
	v_pk_mul_f32 v[38:39], v[38:39], v[170:171]
	v_max_f32_e32 v170, 0.5, v1
	v_cvt_f32_ubyte3_e32 v1, v160
	v_pk_mul_f32 v[172:173], v[174:175], v[184:185]
	v_max_f32_e32 v171, 0.5, v1
	v_cvt_f32_ubyte0_e32 v1, v161
	v_pk_mul_f32 v[42:43], v[42:43], v[172:173]
	v_max_f32_e32 v172, 0.5, v1
	v_cvt_f32_ubyte1_e32 v1, v161
	v_max_f32_e32 v173, 0.5, v1
	v_cvt_f32_ubyte2_e32 v1, v161
	v_max_f32_e32 v160, 0.5, v1
	v_cvt_f32_ubyte3_e32 v1, v161
	v_cvt_f32_ubyte1_e32 v174, v158
	v_max_f32_e32 v161, 0.5, v1
	v_cvt_f32_ubyte0_e32 v1, v158
	v_max_f32_e32 v175, 0.5, v174
	v_cvt_f32_ubyte2_e32 v174, v158
	v_cvt_f32_ubyte3_e32 v158, v158
	v_max_f32_e32 v177, 0.5, v158
	v_cvt_f32_ubyte0_e32 v158, v159
	v_max_f32_e32 v176, 0.5, v174
	v_max_f32_e32 v174, 0.5, v158
	v_cvt_f32_ubyte1_e32 v158, v159
	v_max_f32_e32 v178, 0.5, v158
	v_cvt_f32_ubyte2_e32 v158, v159
	v_max_f32_e32 v1, 0.5, v1
	v_max_f32_e32 v179, 0.5, v158
	v_cvt_f32_ubyte3_e32 v158, v159
	v_max_f32_e32 v184, 0.5, v158
	v_rcp_f32_e32 v158, v1
	v_rcp_f32_e32 v159, v175
	v_rcp_f32_e32 v174, v174
	v_rcp_f32_e32 v175, v178
	v_rcp_f32_e32 v178, v179
	v_rcp_f32_e32 v179, v184
	v_pk_mul_f32 v[158:159], v[168:169], v[158:159]
	v_rcp_f32_e32 v176, v176
	v_rcp_f32_e32 v177, v177
	v_pk_mul_f32 v[32:33], v[32:33], v[158:159]
	v_pk_mul_f32 v[158:159], v[172:173], v[174:175]
	v_cvt_f32_ubyte0_e32 v1, v156
	v_pk_mul_f32 v[28:29], v[28:29], v[158:159]
	v_max_f32_e32 v158, 0.5, v1
	v_cvt_f32_ubyte1_e32 v1, v156
	v_pk_mul_f32 v[160:161], v[160:161], v[178:179]
	v_max_f32_e32 v159, 0.5, v1
	v_cvt_f32_ubyte2_e32 v1, v156
	v_pk_mul_f32 v[30:31], v[30:31], v[160:161]
	v_max_f32_e32 v160, 0.5, v1
	v_cvt_f32_ubyte3_e32 v1, v156
	v_pk_mul_f32 v[168:169], v[170:171], v[176:177]
	v_max_f32_e32 v161, 0.5, v1
	v_cvt_f32_ubyte0_e32 v1, v157
	v_pk_mul_f32 v[34:35], v[34:35], v[168:169]
	v_max_f32_e32 v168, 0.5, v1
	v_cvt_f32_ubyte1_e32 v1, v157
	v_max_f32_e32 v169, 0.5, v1
	v_cvt_f32_ubyte2_e32 v1, v157
	v_max_f32_e32 v156, 0.5, v1
	v_cvt_f32_ubyte3_e32 v1, v157
	v_cvt_f32_ubyte1_e32 v170, v154
	v_max_f32_e32 v157, 0.5, v1
	v_cvt_f32_ubyte0_e32 v1, v154
	v_max_f32_e32 v171, 0.5, v170
	v_cvt_f32_ubyte2_e32 v170, v154
	v_cvt_f32_ubyte3_e32 v154, v154
	v_max_f32_e32 v173, 0.5, v154
	v_cvt_f32_ubyte0_e32 v154, v155
	v_max_f32_e32 v172, 0.5, v170
	v_max_f32_e32 v170, 0.5, v154
	v_cvt_f32_ubyte1_e32 v154, v155
	v_max_f32_e32 v174, 0.5, v154
	v_cvt_f32_ubyte2_e32 v154, v155
	v_max_f32_e32 v1, 0.5, v1
	v_max_f32_e32 v175, 0.5, v154
	v_cvt_f32_ubyte3_e32 v154, v155
	v_max_f32_e32 v176, 0.5, v154
	v_rcp_f32_e32 v154, v1
	v_rcp_f32_e32 v155, v171
	v_rcp_f32_e32 v170, v170
	v_rcp_f32_e32 v171, v174
	v_rcp_f32_e32 v174, v175
	v_rcp_f32_e32 v175, v176
	v_pk_mul_f32 v[154:155], v[158:159], v[154:155]
	v_rcp_f32_e32 v172, v172
	v_rcp_f32_e32 v173, v173
	v_pk_mul_f32 v[24:25], v[24:25], v[154:155]
	v_pk_mul_f32 v[154:155], v[168:169], v[170:171]
	s_waitcnt vmcnt(0)
	v_cvt_f32_ubyte0_e32 v1, v152
	v_pk_mul_f32 v[20:21], v[20:21], v[154:155]
	v_max_f32_e32 v154, 0.5, v1
	v_cvt_f32_ubyte1_e32 v1, v152
	v_pk_mul_f32 v[156:157], v[156:157], v[174:175]
	v_max_f32_e32 v155, 0.5, v1
	v_cvt_f32_ubyte2_e32 v1, v152
	v_pk_mul_f32 v[22:23], v[22:23], v[156:157]
	v_max_f32_e32 v156, 0.5, v1
	v_cvt_f32_ubyte3_e32 v1, v152
	v_pk_mul_f32 v[158:159], v[160:161], v[172:173]
	v_max_f32_e32 v157, 0.5, v1
	v_cvt_f32_ubyte0_e32 v1, v153
	v_pk_mul_f32 v[26:27], v[26:27], v[158:159]
	v_max_f32_e32 v158, 0.5, v1
	v_cvt_f32_ubyte1_e32 v1, v153
	v_max_f32_e32 v159, 0.5, v1
	v_cvt_f32_ubyte2_e32 v1, v153
	v_max_f32_e32 v152, 0.5, v1
	v_cvt_f32_ubyte3_e32 v1, v153
	v_cvt_f32_ubyte1_e32 v160, v150
	v_max_f32_e32 v153, 0.5, v1
	v_cvt_f32_ubyte0_e32 v1, v150
	v_max_f32_e32 v161, 0.5, v160
	v_cvt_f32_ubyte2_e32 v160, v150
	v_cvt_f32_ubyte3_e32 v150, v150
	v_max_f32_e32 v169, 0.5, v150
	v_cvt_f32_ubyte0_e32 v150, v151
	v_max_f32_e32 v168, 0.5, v160
	v_max_f32_e32 v160, 0.5, v150
	v_cvt_f32_ubyte1_e32 v150, v151
	v_max_f32_e32 v170, 0.5, v150
	v_cvt_f32_ubyte2_e32 v150, v151
	v_max_f32_e32 v1, 0.5, v1
	v_max_f32_e32 v171, 0.5, v150
	v_cvt_f32_ubyte3_e32 v150, v151
	v_max_f32_e32 v172, 0.5, v150
	v_rcp_f32_e32 v150, v1
	v_rcp_f32_e32 v151, v161
	v_rcp_f32_e32 v160, v160
	v_rcp_f32_e32 v161, v170
	v_rcp_f32_e32 v170, v171
	v_rcp_f32_e32 v171, v172
	v_pk_mul_f32 v[150:151], v[154:155], v[150:151]
	v_rcp_f32_e32 v168, v168
	v_rcp_f32_e32 v169, v169
	v_pk_mul_f32 v[16:17], v[16:17], v[150:151]
	v_pk_mul_f32 v[150:151], v[158:159], v[160:161]
	v_cvt_f32_ubyte0_e32 v1, v148
	v_pk_mul_f32 v[12:13], v[12:13], v[150:151]
; __device__ __forceinline__ f32x4 un_unorm8(unsigned w) { return (f32x4){fmaxf((float)(w & 255u), 0.5f), fmaxf((float)((w >> 8) & 255u), 0.5f), fmaxf((float)((w >> 16) & 255u), 0.5f), fmaxf((float)(w >> 24), 0.5f)}; }
; #define PG8_STAGE(bufoff, gbase, voff) do { _Pragma("unroll") for (int _i = 0; _i < 2; ++_i) \
;         __builtin_amdgcn_global_load_lds((const unsigned*)((const char*)(gbase) + (voff)[_i]), (LAS unsigned*)(lds + (bufoff) + ldsw + _i * 8192), 16, 0, 0); } while (0)
; #define PG8_LDA(dst, b, h) do { _Pragma("unroll") for (int m = 0; m < 4; ++m) _Pragma("unroll") for (int k = 0; k < 2; ++k) dst[m][k] = *(const LAS bf16x8*)(lds + PG8_SA(b, h) + aoff + m * 2048 + k * 1024); } while (0)
; #define PG8_LDB(dst, b, h) do { _Pragma("unroll") for (int n = 0; n < 2; ++n) _Pragma("unroll") for (int k = 0; k < 2; ++k) dst[n][k] = *(const LAS bf16x8*)(lds + PG8_SB(b, h) + boff + n * 2048 + k * 1024); } while (0)
; #define PG8_WAIT_V(n) asm volatile("s_waitcnt vmcnt(" #n ")" ::: "memory")
; #define PG8_WAIT_L(n) asm volatile("s_waitcnt lgkmcnt(" #n ")" ::: "memory")
; template <class Epi, class Order = StaticOrder, bool HALFN = false>
; __device__ __forceinline__ void gemm_phase(LAS unsigned char* lds, const Gemm g, const Epi& E) {
;     ...
;             const char* a1 = cA + (size_t)(t + 1) * kstep;
;             const char* a2 = last ? nA : cA + (size_t)(t + 2) * kstep; const char* b2 = last ? nB : cB + (size_t)(t + 2) * kstep;
;             const char* a3 = a2 + kstep; const char* b3 = b2 + kstep;
;             PG8_LDB(B0, 0, 0); if constexpr (!HALFN) PG8_LDB(B1, 0, 1); PG8_SCHED; PG8_LDA(At, 0, 0); PG8_STAGE(PG8_SA(1, 1), a1 + hstepA, voffA);
;             PG8_WAIT_V(8); PG8_WAIT_L(0); PG8_BAR; PG8_MMA(0, 0, At, B0); if constexpr (!HALFN) PG8_MMA(0, 1, At, B1); PG8_BAR; PG8_SCHED;
;     __device__ __forceinline__ void seam(f32x4 (&acc)[2][2][4][2], const Unit& u, int n, int wr, int wc, int fr, int fq) const {
;     ...
;                 for (int bj = 0; bj < 2; ++bj) { const f32x4 a0 = un_unorm8(ga[m][bj].x), a1 = un_unorm8(ga[m][bj].y), b0 = un_unorm8(gb[m][bj].x), b1 = un_unorm8(gb[m][bj].y);
; #pragma unroll
;                     for (int j = 0; j < 4; ++j) { acc[ai][bj][m][0][j] *= a0[j] * __builtin_amdgcn_rcpf(b0[j]); acc[ai][bj][m][1][j] *= a1[j] * __builtin_amdgcn_rcpf(b1[j]); } }
;             asm volatile("" ::: "memory");
	v_max_f32_e32 v150, 0.5, v1
	v_cvt_f32_ubyte1_e32 v1, v148
	v_pk_mul_f32 v[152:153], v[152:153], v[170:171]
	v_max_f32_e32 v151, 0.5, v1
	v_cvt_f32_ubyte2_e32 v1, v148
	v_pk_mul_f32 v[14:15], v[14:15], v[152:153]
	v_max_f32_e32 v152, 0.5, v1
	v_cvt_f32_ubyte3_e32 v1, v148
	v_pk_mul_f32 v[154:155], v[156:157], v[168:169]
	v_max_f32_e32 v153, 0.5, v1
	v_cvt_f32_ubyte0_e32 v1, v149
	v_pk_mul_f32 v[18:19], v[18:19], v[154:155]
	v_max_f32_e32 v154, 0.5, v1
	v_cvt_f32_ubyte1_e32 v1, v149
	v_max_f32_e32 v155, 0.5, v1
	v_cvt_f32_ubyte2_e32 v1, v149
	v_max_f32_e32 v148, 0.5, v1
	v_cvt_f32_ubyte3_e32 v1, v149
	v_cvt_f32_ubyte1_e32 v156, v2
	v_max_f32_e32 v149, 0.5, v1
	v_cvt_f32_ubyte0_e32 v1, v2
	v_max_f32_e32 v157, 0.5, v156
	v_cvt_f32_ubyte2_e32 v156, v2
	v_cvt_f32_ubyte3_e32 v2, v2
	v_max_f32_e32 v159, 0.5, v2
	v_cvt_f32_ubyte0_e32 v2, v3
	v_max_f32_e32 v158, 0.5, v156
	v_max_f32_e32 v156, 0.5, v2
	v_cvt_f32_ubyte1_e32 v2, v3
	v_max_f32_e32 v160, 0.5, v2
	v_cvt_f32_ubyte2_e32 v2, v3
	v_max_f32_e32 v1, 0.5, v1
	v_max_f32_e32 v161, 0.5, v2
	v_cvt_f32_ubyte3_e32 v2, v3
	v_max_f32_e32 v168, 0.5, v2
	v_rcp_f32_e32 v2, v1
	v_rcp_f32_e32 v3, v157
	v_rcp_f32_e32 v156, v156
	v_rcp_f32_e32 v158, v158
	v_rcp_f32_e32 v159, v159
	v_rcp_f32_e32 v157, v160
	v_rcp_f32_e32 v160, v161
	v_rcp_f32_e32 v161, v168
	v_pk_mul_f32 v[2:3], v[150:151], v[2:3]
	v_pk_mul_f32 v[150:151], v[152:153], v[158:159]
	v_pk_mul_f32 v[8:9], v[8:9], v[2:3]
	v_pk_mul_f32 v[2:3], v[154:155], v[156:157]
	v_pk_mul_f32 v[148:149], v[148:149], v[160:161]
	v_pk_mul_f32 v[10:11], v[10:11], v[150:151]
	v_pk_mul_f32 v[6:7], v[6:7], v[148:149]
	v_pk_mul_f32 v[4:5], v[4:5], v[2:3]
	s_andn2_b64 vcc, exec, s[44:45]
	s_cbranch_vccnz .Lsm_b
	s_barrier
.Lsm_b:
.LBB0_619:
	s_add_u32 s4, s52, s54
	s_addc_u32 s5, s53, s55
	s_add_u32 s4, s4, 0x100
	s_addc_u32 s5, s5, 0
	s_add_u32 s26, s62, s54
	s_addc_u32 s27, s63, s55
	s_add_i32 s28, 0, 0x10000
	s_cmpk_eq_i32 s54, 0x1700
	s_cselect_b32 s7, s49, s5
	s_cselect_b32 s6, s48, s4
	v_add_u32_e32 v1, s28, v182
	s_cselect_b32 s5, s51, s27
	s_cselect_b32 s4, s50, s26
	s_add_i32 s29, 0, 0x14000
	ds_read_b128 v[148:151], v1
	ds_read_b128 v[152:155], v1 offset:1024
	ds_read_b128 v[156:159], v1 offset:2048
	ds_read_b128 v[168:171], v1 offset:3072
	v_add_u32_e32 v1, s29, v182
	ds_read_b128 v[172:175], v1
	ds_read_b128 v[176:179], v1 offset:1024
	ds_read_b128 v[184:187], v1 offset:2048
	ds_read_b128 v[208:211], v1 offset:3072
	v_lshl_add_u64 v[2:3], v[144:145], 0, s[54:55]
	s_add_i32 m0, s16, 0xc000
	ds_read_b128 v[212:215], v183
	ds_read_b128 v[216:219], v183 offset:1024
	ds_read_b128 v[220:223], v183 offset:2048
	ds_read_b128 v[224:227], v183 offset:3072
	ds_read_b128 v[228:231], v183 offset:4096
	ds_read_b128 v[232:235], v183 offset:5120
	ds_read_b128 v[236:239], v183 offset:6144
	ds_read_b128 v[240:243], v183 offset:7168
	global_load_lds_dwordx4 v[2:3], off
	v_lshl_add_u64 v[2:3], v[146:147], 0, s[54:55]
	s_add_i32 m0, s16, 0xe000
	s_nop 0
	global_load_lds_dwordx4 v[2:3], off
	s_waitcnt vmcnt(8)
	s_waitcnt lgkmcnt(0)
	s_barrier
	s_setprio 1
	s_waitcnt lgkmcnt(0)
	v_mfma_f32_16x16x32_bf16 v[128:131], v[148:151], v[212:215], v[128:131]
	v_mfma_f32_16x16x32_bf16 v[124:127], v[156:159], v[212:215], v[124:127]
	v_mfma_f32_16x16x32_bf16 v[112:115], v[148:151], v[220:223], v[112:115]
	v_mfma_f32_16x16x32_bf16 v[108:111], v[156:159], v[220:223], v[108:111]
	v_mfma_f32_16x16x32_bf16 v[96:99], v[148:151], v[228:231], v[96:99]
	v_mfma_f32_16x16x32_bf16 v[92:95], v[156:159], v[228:231], v[92:95]
	v_mfma_f32_16x16x32_bf16 v[80:83], v[148:151], v[236:239], v[80:83]
	v_mfma_f32_16x16x32_bf16 v[76:79], v[156:159], v[236:239], v[76:79]
	v_mfma_f32_16x16x32_bf16 v[128:131], v[152:155], v[216:219], v[128:131]
	v_mfma_f32_16x16x32_bf16 v[124:127], v[168:171], v[216:219], v[124:127]
	v_mfma_f32_16x16x32_bf16 v[112:115], v[152:155], v[224:227], v[112:115]
	v_mfma_f32_16x16x32_bf16 v[108:111], v[168:171], v[224:227], v[108:111]
	v_mfma_f32_16x16x32_bf16 v[96:99], v[152:155], v[232:235], v[96:99]
	v_mfma_f32_16x16x32_bf16 v[92:95], v[168:171], v[232:235], v[92:95]
	v_mfma_f32_16x16x32_bf16 v[80:83], v[152:155], v[240:243], v[80:83]
	v_mfma_f32_16x16x32_bf16 v[76:79], v[168:171], v[240:243], v[76:79]
	s_setprio 0
	s_setprio 1
	v_mfma_f32_16x16x32_bf16 v[120:123], v[172:175], v[212:215], v[120:123]
	v_mfma_f32_16x16x32_bf16 v[116:119], v[184:187], v[212:215], v[116:119]
	v_mfma_f32_16x16x32_bf16 v[104:107], v[172:175], v[220:223], v[104:107]
	v_mfma_f32_16x16x32_bf16 v[100:103], v[184:187], v[220:223], v[100:103]
	v_mfma_f32_16x16x32_bf16 v[88:91], v[172:175], v[228:231], v[88:91]
	v_mfma_f32_16x16x32_bf16 v[84:87], v[184:187], v[228:231], v[84:87]
	v_mfma_f32_16x16x32_bf16 v[72:75], v[172:175], v[236:239], v[72:75]
	v_mfma_f32_16x16x32_bf16 v[68:71], v[184:187], v[236:239], v[68:71]
	v_mfma_f32_16x16x32_bf16 v[120:123], v[176:179], v[216:219], v[120:123]
	v_mfma_f32_16x16x32_bf16 v[116:119], v[208:211], v[216:219], v[116:119]
	v_mfma_f32_16x16x32_bf16 v[104:107], v[176:179], v[224:227], v[104:107]
	v_mfma_f32_16x16x32_bf16 v[100:103], v[208:211], v[224:227], v[100:103]
	v_mfma_f32_16x16x32_bf16 v[88:91], v[176:179], v[232:235], v[88:91]
	v_mfma_f32_16x16x32_bf16 v[84:87], v[208:211], v[232:235], v[84:87]
	v_mfma_f32_16x16x32_bf16 v[72:75], v[176:179], v[240:243], v[72:75]
	v_mfma_f32_16x16x32_bf16 v[68:71], v[208:211], v[240:243], v[68:71]
	s_setprio 0
	s_barrier
; #define PG8_STAGE(bufoff, gbase, voff) do { _Pragma("unroll") for (int _i = 0; _i < 2; ++_i) \
;         __builtin_amdgcn_global_load_lds((const unsigned*)((const char*)(gbase) + (voff)[_i]), (LAS unsigned*)(lds + (bufoff) + ldsw + _i * 8192), 16, 0, 0); } while (0)
; #define PG8_LDA(dst, b, h) do { _Pragma("unroll") for (int m = 0; m < 4; ++m) _Pragma("unroll") for (int k = 0; k < 2; ++k) dst[m][k] = *(const LAS bf16x8*)(lds + PG8_SA(b, h) + aoff + m * 2048 + k * 1024); } while (0)
; #define PG8_LDB(dst, b, h) do { _Pragma("unroll") for (int n = 0; n < 2; ++n) _Pragma("unroll") for (int k = 0; k < 2; ++k) dst[n][k] = *(const LAS bf16x8*)(lds + PG8_SB(b, h) + boff + n * 2048 + k * 1024); } while (0)
; #define PG8_MMA(ai, bj, At, Bt) do { __builtin_amdgcn_s_setprio(1); _Pragma("unroll") for (int m = 0; m < 4; ++m) _Pragma("unroll") for (int n = 0; n < 2; ++n) _Pragma("unroll") for (int k = 0; k < 2; ++k) \
;         acc[ai][bj][m][n] = __builtin_amdgcn_mfma_f32_16x16x32_bf16(Bt[n][k], At[m][k], acc[ai][bj][m][n], 0, 0, 0); __builtin_amdgcn_s_setprio(0); } while (0)
; #define PG8_WAIT_V(n) asm volatile("s_waitcnt vmcnt(" #n ")" ::: "memory")
; #define PG8_WAIT_L(n) asm volatile("s_waitcnt lgkmcnt(" #n ")" ::: "memory")
; #define PG8_BAR __builtin_amdgcn_s_barrier()
; #define PG8_SCHED __builtin_amdgcn_sched_barrier(0)
; template <class Epi, class Order = StaticOrder, bool HALFN = false>
; __device__ __forceinline__ void gemm_phase(LAS unsigned char* lds, const Gemm g, const Epi& E) {
;     ...
;             PG8_WAIT_V(8); PG8_WAIT_L(0); PG8_BAR; PG8_MMA(0, 0, At, B0); if constexpr (!HALFN) PG8_MMA(0, 1, At, B1); PG8_BAR; PG8_SCHED;
;             PG8_LDA(At, 0, 1); PG8_STAGE(PG8_SB(0, 0), b2, voffB); PG8_STAGE(PG8_SB(0, 1), b2 + hstepB, voffB); PG8_STAGE(PG8_SA(0, 0), a2, voffA);
;             PG8_WAIT_V(8); PG8_WAIT_L(0); PG8_BAR; PG8_MMA(1, 0, At, B0); if constexpr (!HALFN) PG8_MMA(1, 1, At, B1); PG8_BAR; PG8_SCHED;
;             PG8_LDB(B0, 1, 0); if constexpr (!HALFN) PG8_LDB(B1, 1, 1); PG8_SCHED; PG8_LDA(At, 1, 0); PG8_STAGE(PG8_SA(0, 1), a2 + hstepA, voffA);
	s_add_i32 s26, s28, s15
	v_lshl_add_u64 v[160:161], s[4:5], 0, v[134:135]
	s_mov_b32 m0, s26
	ds_read_b128 v[212:215], v183 offset:16384
	ds_read_b128 v[216:219], v183 offset:17408
	ds_read_b128 v[220:223], v183 offset:18432
	ds_read_b128 v[224:227], v183 offset:19456
	ds_read_b128 v[228:231], v183 offset:20480
	ds_read_b128 v[232:235], v183 offset:21504
	ds_read_b128 v[236:239], v183 offset:22528
	ds_read_b128 v[240:243], v183 offset:23552
	global_load_lds_dwordx4 v[160:161], off
	s_add_i32 m0, s26, 0x2000
	s_add_u32 s26, s4, 0xc0000
	v_lshl_add_u64 v[244:245], s[4:5], 0, v[138:139]
	s_addc_u32 s27, s5, 0
	s_add_i32 s28, s29, s15
	global_load_lds_dwordx4 v[244:245], off
	v_lshl_add_u64 v[2:3], s[26:27], 0, v[134:135]
	s_mov_b32 m0, s28
	v_lshl_add_u64 v[246:247], s[6:7], 0, v[132:133]
	global_load_lds_dwordx4 v[2:3], off
	v_lshl_add_u64 v[2:3], s[26:27], 0, v[138:139]
	s_add_i32 m0, s28, 0x2000
	v_lshl_add_u64 v[248:249], s[6:7], 0, v[136:137]
	global_load_lds_dwordx4 v[2:3], off
	s_mov_b32 m0, s16
	s_nop 0
	global_load_lds_dwordx4 v[246:247], off
	s_mov_b32 m0, s17
	s_nop 0
	global_load_lds_dwordx4 v[248:249], off
	s_waitcnt vmcnt(8)
	s_waitcnt lgkmcnt(0)
	s_barrier
	s_setprio 1
	s_waitcnt lgkmcnt(0)
	v_mfma_f32_16x16x32_bf16 v[64:67], v[148:151], v[212:215], v[64:67]
	v_mfma_f32_16x16x32_bf16 v[60:63], v[156:159], v[212:215], v[60:63]
	v_mfma_f32_16x16x32_bf16 v[48:51], v[148:151], v[220:223], v[48:51]
	v_mfma_f32_16x16x32_bf16 v[44:47], v[156:159], v[220:223], v[44:47]
	v_mfma_f32_16x16x32_bf16 v[32:35], v[148:151], v[228:231], v[32:35]
	v_mfma_f32_16x16x32_bf16 v[28:31], v[156:159], v[228:231], v[28:31]
	v_mfma_f32_16x16x32_bf16 v[16:19], v[148:151], v[236:239], v[16:19]
	v_mfma_f32_16x16x32_bf16 v[12:15], v[156:159], v[236:239], v[12:15]
	v_mfma_f32_16x16x32_bf16 v[64:67], v[152:155], v[216:219], v[64:67]
	v_mfma_f32_16x16x32_bf16 v[60:63], v[168:171], v[216:219], v[60:63]
	v_mfma_f32_16x16x32_bf16 v[48:51], v[152:155], v[224:227], v[48:51]
	v_mfma_f32_16x16x32_bf16 v[44:47], v[168:171], v[224:227], v[44:47]
	v_mfma_f32_16x16x32_bf16 v[32:35], v[152:155], v[232:235], v[32:35]
	v_mfma_f32_16x16x32_bf16 v[28:31], v[168:171], v[232:235], v[28:31]
	v_mfma_f32_16x16x32_bf16 v[16:19], v[152:155], v[240:243], v[16:19]
	v_mfma_f32_16x16x32_bf16 v[12:15], v[168:171], v[240:243], v[12:15]
	s_setprio 0
	s_setprio 1
	v_mfma_f32_16x16x32_bf16 v[56:59], v[172:175], v[212:215], v[56:59]
	v_mfma_f32_16x16x32_bf16 v[52:55], v[184:187], v[212:215], v[52:55]
	v_mfma_f32_16x16x32_bf16 v[40:43], v[172:175], v[220:223], v[40:43]
	v_mfma_f32_16x16x32_bf16 v[36:39], v[184:187], v[220:223], v[36:39]
	v_mfma_f32_16x16x32_bf16 v[24:27], v[172:175], v[228:231], v[24:27]
	v_mfma_f32_16x16x32_bf16 v[20:23], v[184:187], v[228:231], v[20:23]
	v_mfma_f32_16x16x32_bf16 v[8:11], v[172:175], v[236:239], v[8:11]
	v_mfma_f32_16x16x32_bf16 v[2:5], v[184:187], v[236:239], v[4:7]
	v_mfma_f32_16x16x32_bf16 v[56:59], v[176:179], v[216:219], v[56:59]
	v_mfma_f32_16x16x32_bf16 v[52:55], v[208:211], v[216:219], v[52:55]
	v_mfma_f32_16x16x32_bf16 v[40:43], v[176:179], v[224:227], v[40:43]
	v_mfma_f32_16x16x32_bf16 v[36:39], v[208:211], v[224:227], v[36:39]
	v_mfma_f32_16x16x32_bf16 v[24:27], v[176:179], v[232:235], v[24:27]
	v_mfma_f32_16x16x32_bf16 v[20:23], v[208:211], v[232:235], v[20:23]
	v_mfma_f32_16x16x32_bf16 v[8:11], v[176:179], v[240:243], v[8:11]
	v_mfma_f32_16x16x32_bf16 v[2:5], v[208:211], v[240:243], v[2:5]
	s_setprio 0
	s_barrier
	s_add_i32 s26, 0, 0x18000
	v_add_u32_e32 v1, s26, v182
	s_add_i32 s27, 0, 0x1c000
	ds_read_b128 v[148:151], v1
	ds_read_b128 v[152:155], v1 offset:1024
	ds_read_b128 v[156:159], v1 offset:2048
	ds_read_b128 v[168:171], v1 offset:3072
	v_add_u32_e32 v1, s27, v182
	ds_read_b128 v[172:175], v1
	ds_read_b128 v[176:179], v1 offset:1024
	ds_read_b128 v[184:187], v1 offset:2048
	ds_read_b128 v[208:211], v1 offset:3072
	s_add_u32 s6, s6, 0xc0000
	s_addc_u32 s7, s7, 0
	s_mov_b32 m0, s18
	v_lshl_add_u64 v[6:7], s[6:7], 0, v[132:133]
	ds_read_b128 v[212:215], v183 offset:32768
	ds_read_b128 v[216:219], v183 offset:33792
	ds_read_b128 v[220:223], v183 offset:34816
	ds_read_b128 v[224:227], v183 offset:35840
	ds_read_b128 v[228:231], v183 offset:36864
	ds_read_b128 v[232:235], v183 offset:37888
	ds_read_b128 v[236:239], v183 offset:38912
	ds_read_b128 v[240:243], v183 offset:39936
	global_load_lds_dwordx4 v[6:7], off
	v_lshl_add_u64 v[6:7], s[6:7], 0, v[136:137]
	s_mov_b32 m0, s19
	s_nop 0
	global_load_lds_dwordx4 v[6:7], off
	s_waitcnt vmcnt(8)
	s_waitcnt lgkmcnt(0)
	s_barrier
; #define PG8_STAGE(bufoff, gbase, voff) do { _Pragma("unroll") for (int _i = 0; _i < 2; ++_i) \
;         __builtin_amdgcn_global_load_lds((const unsigned*)((const char*)(gbase) + (voff)[_i]), (LAS unsigned*)(lds + (bufoff) + ldsw + _i * 8192), 16, 0, 0); } while (0)
; #define PG8_LDA(dst, b, h) do { _Pragma("unroll") for (int m = 0; m < 4; ++m) _Pragma("unroll") for (int k = 0; k < 2; ++k) dst[m][k] = *(const LAS bf16x8*)(lds + PG8_SA(b, h) + aoff + m * 2048 + k * 1024); } while (0)
; #define PG8_LDB(dst, b, h) do { _Pragma("unroll") for (int n = 0; n < 2; ++n) _Pragma("unroll") for (int k = 0; k < 2; ++k) dst[n][k] = *(const LAS bf16x8*)(lds + PG8_SB(b, h) + boff + n * 2048 + k * 1024); } while (0)
; #define PG8_MMA(ai, bj, At, Bt) do { __builtin_amdgcn_s_setprio(1); _Pragma("unroll") for (int m = 0; m < 4; ++m) _Pragma("unroll") for (int n = 0; n < 2; ++n) _Pragma("unroll") for (int k = 0; k < 2; ++k) \
;         acc[ai][bj][m][n] = __builtin_amdgcn_mfma_f32_16x16x32_bf16(Bt[n][k], At[m][k], acc[ai][bj][m][n], 0, 0, 0); __builtin_amdgcn_s_setprio(0); } while (0)
; #define PG8_WAIT_V(n) asm volatile("s_waitcnt vmcnt(" #n ")" ::: "memory")
; #define PG8_WAIT_L(n) asm volatile("s_waitcnt lgkmcnt(" #n ")" ::: "memory")
; #define PG8_BAR __builtin_amdgcn_s_barrier()
; #define PG8_SCHED __builtin_amdgcn_sched_barrier(0)
; template <class Epi, class Order = StaticOrder, bool HALFN = false>
; __device__ __forceinline__ void gemm_phase(LAS unsigned char* lds, const Gemm g, const Epi& E) {
;     ...
;             PG8_WAIT_V(8); PG8_WAIT_L(0); PG8_BAR; PG8_MMA(1, 0, At, B0); if constexpr (!HALFN) PG8_MMA(1, 1, At, B1); PG8_BAR; PG8_SCHED;
;             PG8_LDB(B0, 1, 0); if constexpr (!HALFN) PG8_LDB(B1, 1, 1); PG8_SCHED; PG8_LDA(At, 1, 0); PG8_STAGE(PG8_SA(0, 1), a2 + hstepA, voffA);
;             PG8_WAIT_V(8); PG8_WAIT_L(0); PG8_BAR; PG8_MMA(0, 0, At, B0); if constexpr (!HALFN) PG8_MMA(0, 1, At, B1); PG8_BAR; PG8_SCHED;
;             PG8_LDA(At, 1, 1); PG8_STAGE(PG8_SB(1, 0), b3, voffB); PG8_STAGE(PG8_SB(1, 1), b3 + hstepB, voffB); PG8_STAGE(PG8_SA(1, 0), a3, voffA);
;             PG8_WAIT_V(8); PG8_WAIT_L(0); PG8_BAR; PG8_MMA(1, 0, At, B0); if constexpr (!HALFN) PG8_MMA(1, 1, At, B1); PG8_BAR; PG8_SCHED;
;         }
	s_setprio 1
	s_waitcnt lgkmcnt(0)
	v_mfma_f32_16x16x32_bf16 v[128:131], v[148:151], v[212:215], v[128:131]
	v_mfma_f32_16x16x32_bf16 v[124:127], v[156:159], v[212:215], v[124:127]
	v_mfma_f32_16x16x32_bf16 v[112:115], v[148:151], v[220:223], v[112:115]
	v_mfma_f32_16x16x32_bf16 v[108:111], v[156:159], v[220:223], v[108:111]
	v_mfma_f32_16x16x32_bf16 v[96:99], v[148:151], v[228:231], v[96:99]
	v_mfma_f32_16x16x32_bf16 v[92:95], v[156:159], v[228:231], v[92:95]
	v_mfma_f32_16x16x32_bf16 v[80:83], v[148:151], v[236:239], v[80:83]
	v_mfma_f32_16x16x32_bf16 v[76:79], v[156:159], v[236:239], v[76:79]
	v_mfma_f32_16x16x32_bf16 v[128:131], v[152:155], v[216:219], v[128:131]
	v_mfma_f32_16x16x32_bf16 v[124:127], v[168:171], v[216:219], v[124:127]
	v_mfma_f32_16x16x32_bf16 v[112:115], v[152:155], v[224:227], v[112:115]
	v_mfma_f32_16x16x32_bf16 v[108:111], v[168:171], v[224:227], v[108:111]
	v_mfma_f32_16x16x32_bf16 v[96:99], v[152:155], v[232:235], v[96:99]
	v_mfma_f32_16x16x32_bf16 v[92:95], v[168:171], v[232:235], v[92:95]
	v_mfma_f32_16x16x32_bf16 v[80:83], v[152:155], v[240:243], v[80:83]
	v_mfma_f32_16x16x32_bf16 v[76:79], v[168:171], v[240:243], v[76:79]
	s_setprio 0
	s_setprio 1
	v_mfma_f32_16x16x32_bf16 v[120:123], v[172:175], v[212:215], v[120:123]
	v_mfma_f32_16x16x32_bf16 v[116:119], v[184:187], v[212:215], v[116:119]
	v_mfma_f32_16x16x32_bf16 v[104:107], v[172:175], v[220:223], v[104:107]
	v_mfma_f32_16x16x32_bf16 v[100:103], v[184:187], v[220:223], v[100:103]
	v_mfma_f32_16x16x32_bf16 v[88:91], v[172:175], v[228:231], v[88:91]
	v_mfma_f32_16x16x32_bf16 v[84:87], v[184:187], v[228:231], v[84:87]
	v_mfma_f32_16x16x32_bf16 v[72:75], v[172:175], v[236:239], v[72:75]
	v_mfma_f32_16x16x32_bf16 v[68:71], v[184:187], v[236:239], v[68:71]
	v_mfma_f32_16x16x32_bf16 v[120:123], v[176:179], v[216:219], v[120:123]
	v_mfma_f32_16x16x32_bf16 v[116:119], v[208:211], v[216:219], v[116:119]
	v_mfma_f32_16x16x32_bf16 v[104:107], v[176:179], v[224:227], v[104:107]
	v_mfma_f32_16x16x32_bf16 v[100:103], v[208:211], v[224:227], v[100:103]
	v_mfma_f32_16x16x32_bf16 v[88:91], v[176:179], v[232:235], v[88:91]
	v_mfma_f32_16x16x32_bf16 v[84:87], v[208:211], v[232:235], v[84:87]
	v_mfma_f32_16x16x32_bf16 v[72:75], v[176:179], v[240:243], v[72:75]
	v_mfma_f32_16x16x32_bf16 v[68:71], v[208:211], v[240:243], v[68:71]
	s_setprio 0
	s_barrier
	s_add_i32 s6, s26, s15
	v_lshl_add_u64 v[6:7], v[160:161], 0, s[60:61]
	s_mov_b32 m0, s6
	ds_read_b128 v[212:215], v183 offset:49152
	ds_read_b128 v[216:219], v183 offset:50176
	ds_read_b128 v[220:223], v183 offset:51200
	ds_read_b128 v[224:227], v183 offset:52224
	ds_read_b128 v[228:231], v183 offset:53248
	ds_read_b128 v[232:235], v183 offset:54272
	ds_read_b128 v[236:239], v183 offset:55296
	ds_read_b128 v[240:243], v183 offset:56320
	global_load_lds_dwordx4 v[6:7], off
	s_add_i32 m0, s6, 0x2000
	s_add_u32 s4, s4, 0xc0080
	v_lshl_add_u64 v[6:7], v[244:245], 0, s[60:61]
	s_addc_u32 s5, s5, 0
	s_add_i32 s6, s27, s15
	global_load_lds_dwordx4 v[6:7], off
	v_lshl_add_u64 v[6:7], s[4:5], 0, v[134:135]
	s_mov_b32 m0, s6
	s_nop 0
	global_load_lds_dwordx4 v[6:7], off
	v_lshl_add_u64 v[6:7], s[4:5], 0, v[138:139]
	s_add_i32 m0, s6, 0x2000
	s_nop 0
	global_load_lds_dwordx4 v[6:7], off
	v_lshl_add_u64 v[6:7], v[246:247], 0, s[60:61]
	s_mov_b32 m0, s22
	s_nop 0
	global_load_lds_dwordx4 v[6:7], off
	v_lshl_add_u64 v[6:7], v[248:249], 0, s[60:61]
	s_mov_b32 m0, s23
	s_nop 0
	global_load_lds_dwordx4 v[6:7], off
	s_waitcnt vmcnt(8)
	s_waitcnt lgkmcnt(0)
	s_barrier
	s_setprio 1
	s_waitcnt lgkmcnt(0)
	v_mfma_f32_16x16x32_bf16 v[64:67], v[148:151], v[212:215], v[64:67]
	v_mfma_f32_16x16x32_bf16 v[60:63], v[156:159], v[212:215], v[60:63]
	v_mfma_f32_16x16x32_bf16 v[48:51], v[148:151], v[220:223], v[48:51]
	v_mfma_f32_16x16x32_bf16 v[44:47], v[156:159], v[220:223], v[44:47]
	v_mfma_f32_16x16x32_bf16 v[32:35], v[148:151], v[228:231], v[32:35]
	v_mfma_f32_16x16x32_bf16 v[28:31], v[156:159], v[228:231], v[28:31]
	v_mfma_f32_16x16x32_bf16 v[16:19], v[148:151], v[236:239], v[16:19]
	v_mfma_f32_16x16x32_bf16 v[12:15], v[156:159], v[236:239], v[12:15]
	v_mfma_f32_16x16x32_bf16 v[64:67], v[152:155], v[216:219], v[64:67]
	v_mfma_f32_16x16x32_bf16 v[60:63], v[168:171], v[216:219], v[60:63]
	v_mfma_f32_16x16x32_bf16 v[48:51], v[152:155], v[224:227], v[48:51]
	v_mfma_f32_16x16x32_bf16 v[44:47], v[168:171], v[224:227], v[44:47]
	v_mfma_f32_16x16x32_bf16 v[32:35], v[152:155], v[232:235], v[32:35]
	v_mfma_f32_16x16x32_bf16 v[28:31], v[168:171], v[232:235], v[28:31]
	v_mfma_f32_16x16x32_bf16 v[16:19], v[152:155], v[240:243], v[16:19]
	v_mfma_f32_16x16x32_bf16 v[12:15], v[168:171], v[240:243], v[12:15]
	s_setprio 0
	s_setprio 1
	v_mfma_f32_16x16x32_bf16 v[56:59], v[172:175], v[212:215], v[56:59]
	v_mfma_f32_16x16x32_bf16 v[52:55], v[184:187], v[212:215], v[52:55]
	v_mfma_f32_16x16x32_bf16 v[40:43], v[172:175], v[220:223], v[40:43]
	v_mfma_f32_16x16x32_bf16 v[36:39], v[184:187], v[220:223], v[36:39]
	v_mfma_f32_16x16x32_bf16 v[24:27], v[172:175], v[228:231], v[24:27]
	v_mfma_f32_16x16x32_bf16 v[20:23], v[184:187], v[228:231], v[20:23]
	v_mfma_f32_16x16x32_bf16 v[6:9], v[172:175], v[236:239], v[8:11]
	v_mfma_f32_16x16x32_bf16 v[2:5], v[184:187], v[236:239], v[2:5]
	v_mfma_f32_16x16x32_bf16 v[56:59], v[176:179], v[216:219], v[56:59]
	v_mfma_f32_16x16x32_bf16 v[52:55], v[208:211], v[216:219], v[52:55]
	v_mfma_f32_16x16x32_bf16 v[40:43], v[176:179], v[224:227], v[40:43]
	v_mfma_f32_16x16x32_bf16 v[36:39], v[208:211], v[224:227], v[36:39]
	v_mfma_f32_16x16x32_bf16 v[24:27], v[176:179], v[232:235], v[24:27]
	v_mfma_f32_16x16x32_bf16 v[20:23], v[208:211], v[232:235], v[20:23]
	v_mfma_f32_16x16x32_bf16 v[8:11], v[176:179], v[240:243], v[6:9]
	v_mfma_f32_16x16x32_bf16 v[4:7], v[208:211], v[240:243], v[2:5]
	s_setprio 0
	s_barrier
	s_add_i32 s4, s74, 2
	s_add_u32 s54, s54, 0x100
	s_addc_u32 s55, s55, 0
	s_cmp_gt_u32 s74, 45
	s_cbranch_scc1 .LBB0_621
	s_mov_b32 s74, s4
	s_cmp_lt_i32 s74, 32
	s_cbranch_scc1 .LBB0_615
	s_branch .LBB0_614
